# grid barrier: local workgroups poll the cross-XCD release word directly (skips the per-XCD relay hop)
# speedup vs baseline: 1.0143x; 1.0002x over previous
.LBB0_2108:
	s_or_b64 exec, exec, s[6:7]
	v_cvt_f32_u32_e32 v4, v2
	s_waitcnt vmcnt(0)
	v_readfirstlane_b32 s4, v3
	v_sub_u32_e32 v3, 0, v2
	v_rcp_iflag_f32_e32 v4, v4
	v_add_u32_e32 v5, s4, v1
	v_mul_f32_e32 v4, 0x4f7ffffe, v4
	v_cvt_u32_f32_e32 v4, v4
	v_mul_lo_u32 v1, v3, v4
	v_mul_hi_u32 v1, v4, v1
	v_add_u32_e32 v1, v4, v1
	v_mul_hi_u32 v1, v5, v1
	v_mul_lo_u32 v3, v1, v2
	v_sub_u32_e32 v3, v5, v3
	v_add_u32_e32 v4, 1, v1
	v_cmp_ge_u32_e32 vcc, v3, v2
	s_nop 1
	v_cndmask_b32_e32 v1, v1, v4, vcc
	v_sub_u32_e32 v4, v3, v2
	v_cndmask_b32_e32 v3, v3, v4, vcc
	v_add_u32_e32 v4, 1, v1
	v_cmp_ge_u32_e32 vcc, v3, v2
	v_add_u32_e32 v3, 1, v5
	s_nop 0
	v_cndmask_b32_e32 v1, v1, v4, vcc
	v_mul_lo_u32 v4, v2, v1
	v_add_u32_e32 v2, v4, v2
	v_cmp_ne_u32_e32 vcc, v3, v2
	s_and_saveexec_b64 s[4:5], vcc
	s_xor_b64 s[4:5], exec, s[4:5]
	s_cbranch_execz .LBB0_2127
	s_waitcnt lgkmcnt(0)
	v_readlane_b32 s8, v254, 13
	v_readlane_b32 s9, v254, 14
	s_nop 4
	global_load_dword v0, v113, s[8:9] sc1
	s_waitcnt vmcnt(0)
	v_cmp_eq_u32_e32 vcc, v0, v1
	s_and_saveexec_b64 s[6:7], vcc
	s_cbranch_execz .LBB0_2126
	s_mov_b32 s20, 1
	s_mov_b64 s[10:11], 0
	s_branch .LBB0_2112
